# attention: hand-scheduled j-loop (direct bias-tile accumulator init, max3 trees, hoisted LDS address math) + batched ZA loads in epilogue
# speedup vs baseline: 1.0100x; 1.0100x over previous
; __device__ __forceinline__ unsigned cvt_pk_bf16(float lo, float hi) { unsigned r; asm volatile("v_cvt_pk_bf16_f32 %0, %1, %2" : "=v"(r) : "v"(lo), "v"(hi)); return r; }
; __device__ __forceinline__ float bflo(unsigned w) { return __uint_as_float(w << 16); }
; __device__ __forceinline__ float bfhi(unsigned w) { return __uint_as_float(w & 0xffff0000u); }
; __device__ __forceinline__ float fexp2(float x) { return __builtin_amdgcn_exp2f(x); }
; __device__ __forceinline__ float half_swap_sum(float v) { const auto rr = __builtin_amdgcn_permlane32_swap(__float_as_uint(v), __float_as_uint(v), false, false); return __uint_as_float(rr[0]) + __uint_as_float(rr[1]); }
; __device__ __forceinline__ void attn_compute(Frame& F, int id) {
;     ...
; #pragma unroll
;     for (int qb = 0; qb < 2; ++qb) {
;         const float mq = qb ? m1 : m0; float lt = half_swap_sum(qb ? l1 : l0); lt += fexp2(sk - mq);
;         const float inv = 1.0f / lt; const size_t tok = tok0 + 32 * qb;
; #pragma unroll
;         for (int dh = 0; dh < 2; ++dh)
; #pragma unroll
;             for (int gq = 0; gq < 4; ++gq) {
;                 const int d = 32 * dh + 8 * gq + 4 * hh;
;                 const v2u z = *(const v2u*)(ZA + tok * 512 + h * 64 + d);
;                 const f32x16& o = qb ? O1[dh] : O0[dh];
;                 v2u w; w.x = pg8::cvt_pk_bf16(o[4 * gq + 0] * inv * bflo(z.x), o[4 * gq + 1] * inv * bfhi(z.x));
;                 w.y = pg8::cvt_pk_bf16(o[4 * gq + 2] * inv * bflo(z.y), o[4 * gq + 3] * inv * bfhi(z.y));
;                 *(v2u*)(A5 + tok * 1024 + h * 64 + d) = w;
.LBB0_544:
	s_lshl_b32 s14, s22, 1
	s_add_u32 s4, s39, s14
	s_addc_u32 s5, s40, 0
	s_add_u32 s22, s37, s14
	s_addc_u32 s23, s38, 0
	v_mov_b32_e32 v203, v2
	v_lshl_add_u64 v[4:5], s[4:5], 0, v[206:207]
	v_lshl_add_u64 v[4:5], v[4:5], 0, v[202:203]
	global_load_dwordx2 v[82:83], v[4:5], off
	global_load_dwordx2 v[84:85], v[4:5], off offset:16
	global_load_dwordx2 v[86:87], v[4:5], off offset:32
	global_load_dwordx2 v[88:89], v[4:5], off offset:48
	global_load_dwordx2 v[90:91], v[4:5], off offset:64
	global_load_dwordx2 v[92:93], v[4:5], off offset:80
	global_load_dwordx2 v[94:95], v[4:5], off offset:96
	global_load_dwordx2 v[96:97], v[4:5], off offset:112
	v_lshlrev_b64 v[10:11], 11, v[204:205]
	v_or_b32_e32 v204, 32, v204
	v_lshlrev_b64 v[8:9], 10, v[204:205]
	v_lshl_add_u64 v[8:9], s[4:5], 0, v[8:9]
	v_lshl_add_u64 v[8:9], v[8:9], 0, v[202:203]
	global_load_dwordx2 v[98:99], v[8:9], off
	global_load_dwordx2 v[100:101], v[8:9], off offset:16
	global_load_dwordx2 v[102:103], v[8:9], off offset:32
	global_load_dwordx2 v[104:105], v[8:9], off offset:48
	global_load_dwordx2 v[106:107], v[8:9], off offset:64
	global_load_dwordx2 v[108:109], v[8:9], off offset:80
	global_load_dwordx2 v[110:111], v[8:9], off offset:96
	global_load_dwordx2 v[112:113], v[8:9], off offset:112
	v_lshl_add_u64 v[10:11], s[22:23], 0, v[10:11]
	v_lshl_add_u64 v[10:11], v[10:11], 0, v[202:203]
	v_lshlrev_b64 v[16:17], 11, v[204:205]
	v_lshl_add_u64 v[16:17], s[22:23], 0, v[16:17]
	v_lshl_add_u64 v[16:17], v[16:17], 0, v[202:203]
	s_mov_b32 s33, s44
	v_sub_f32_e32 v8, v244, v249
	v_exp_f32_e32 v8, v8
	v_mov_b32_e32 v3, v246
	s_nop 1
	v_permlane32_swap_b32_e32 v246, v3
	v_add_f32_e32 v3, v246, v3
	v_add_f32_e32 v3, v8, v3
	v_div_scale_f32 v8, vcc, v3, v3, 1.0
	v_rcp_f32_e32 v9, v8
	v_div_scale_f32 v12, vcc, 1.0, v3, 1.0
	v_fma_f32 v13, -v8, v9, 1.0
	v_fmac_f32_e32 v9, v13, v9
	v_mul_f32_e32 v13, v12, v9
	v_fma_f32 v14, -v8, v13, v12
	v_fmac_f32_e32 v13, v14, v9
	v_fma_f32 v8, -v8, v13, v12
	v_div_fmas_f32 v8, v8, v9, v13
	v_div_fixup_f32 v3, v8, v3, 1.0
	v_mul_f32_e32 v12, v66, v3
	v_mul_f32_e32 v13, v67, v3
	v_mul_f32_e32 v14, v68, v3
	v_mul_f32_e32 v15, v69, v3
	s_waitcnt vmcnt(15)
	v_lshlrev_b32_e32 v4, 16, v82
	v_and_b32_e32 v5, 0xffff0000, v82
	v_lshlrev_b32_e32 v6, 16, v83
	v_and_b32_e32 v7, 0xffff0000, v83
	v_mul_f32_e32 v4, v12, v4
	v_mul_f32_e32 v5, v13, v5
	v_mul_f32_e32 v6, v14, v6
	v_mul_f32_e32 v7, v15, v7
	v_cvt_pk_bf16_f32 v82, v4, v5
	v_cvt_pk_bf16_f32 v83, v6, v7
	global_store_dwordx2 v[10:11], v[82:83], off
	v_mul_f32_e32 v12, v70, v3
	v_mul_f32_e32 v13, v71, v3
	v_mul_f32_e32 v14, v72, v3
	v_mul_f32_e32 v15, v73, v3
	s_waitcnt vmcnt(15)
	v_lshlrev_b32_e32 v4, 16, v84
	v_and_b32_e32 v5, 0xffff0000, v84
	v_lshlrev_b32_e32 v6, 16, v85
	v_and_b32_e32 v7, 0xffff0000, v85
	v_mul_f32_e32 v4, v12, v4
	v_mul_f32_e32 v5, v13, v5
	v_mul_f32_e32 v6, v14, v6
	v_mul_f32_e32 v7, v15, v7
	v_cvt_pk_bf16_f32 v84, v4, v5
	v_cvt_pk_bf16_f32 v85, v6, v7
	global_store_dwordx2 v[10:11], v[84:85], off offset:16
	v_mul_f32_e32 v12, v74, v3
	v_mul_f32_e32 v13, v75, v3
	v_mul_f32_e32 v14, v76, v3
	v_mul_f32_e32 v15, v77, v3
	s_waitcnt vmcnt(15)
	v_lshlrev_b32_e32 v4, 16, v86
	v_and_b32_e32 v5, 0xffff0000, v86
	v_lshlrev_b32_e32 v6, 16, v87
	v_and_b32_e32 v7, 0xffff0000, v87
	v_mul_f32_e32 v4, v12, v4
	v_mul_f32_e32 v5, v13, v5
	v_mul_f32_e32 v6, v14, v6
	v_mul_f32_e32 v7, v15, v7
	v_cvt_pk_bf16_f32 v86, v4, v5
	v_cvt_pk_bf16_f32 v87, v6, v7
	global_store_dwordx2 v[10:11], v[86:87], off offset:32
	v_mul_f32_e32 v12, v78, v3
	v_mul_f32_e32 v13, v79, v3
	v_mul_f32_e32 v14, v80, v3
	v_mul_f32_e32 v15, v81, v3
	s_waitcnt vmcnt(15)
	v_lshlrev_b32_e32 v4, 16, v88
	v_and_b32_e32 v5, 0xffff0000, v88
	v_lshlrev_b32_e32 v6, 16, v89
	v_and_b32_e32 v7, 0xffff0000, v89
	v_mul_f32_e32 v4, v12, v4
	v_mul_f32_e32 v5, v13, v5
	v_mul_f32_e32 v6, v14, v6
	v_mul_f32_e32 v7, v15, v7
	v_cvt_pk_bf16_f32 v88, v4, v5
	v_cvt_pk_bf16_f32 v89, v6, v7
	global_store_dwordx2 v[10:11], v[88:89], off offset:48
	v_mul_f32_e32 v12, v50, v3
	v_mul_f32_e32 v13, v51, v3
	v_mul_f32_e32 v14, v52, v3
	v_mul_f32_e32 v15, v53, v3
	s_waitcnt vmcnt(15)
	v_lshlrev_b32_e32 v4, 16, v90
	v_and_b32_e32 v5, 0xffff0000, v90
	v_lshlrev_b32_e32 v6, 16, v91
	v_and_b32_e32 v7, 0xffff0000, v91
	v_mul_f32_e32 v4, v12, v4
	v_mul_f32_e32 v5, v13, v5
	v_mul_f32_e32 v6, v14, v6
	v_mul_f32_e32 v7, v15, v7
	v_cvt_pk_bf16_f32 v90, v4, v5
	v_cvt_pk_bf16_f32 v91, v6, v7
	global_store_dwordx2 v[10:11], v[90:91], off offset:64
	v_mul_f32_e32 v12, v54, v3
	v_mul_f32_e32 v13, v55, v3
	v_mul_f32_e32 v14, v56, v3
	v_mul_f32_e32 v15, v57, v3
	s_waitcnt vmcnt(15)
	v_lshlrev_b32_e32 v4, 16, v92
	v_and_b32_e32 v5, 0xffff0000, v92
	v_lshlrev_b32_e32 v6, 16, v93
	v_and_b32_e32 v7, 0xffff0000, v93
	v_mul_f32_e32 v4, v12, v4
	v_mul_f32_e32 v5, v13, v5
	v_mul_f32_e32 v6, v14, v6
	v_mul_f32_e32 v7, v15, v7
	v_cvt_pk_bf16_f32 v92, v4, v5
	v_cvt_pk_bf16_f32 v93, v6, v7
	global_store_dwordx2 v[10:11], v[92:93], off offset:80
	v_mul_f32_e32 v12, v58, v3
	v_mul_f32_e32 v13, v59, v3
	v_mul_f32_e32 v14, v60, v3
	v_mul_f32_e32 v15, v61, v3
	s_waitcnt vmcnt(15)
; __device__ __forceinline__ unsigned cvt_pk_bf16(float lo, float hi) { unsigned r; asm volatile("v_cvt_pk_bf16_f32 %0, %1, %2" : "=v"(r) : "v"(lo), "v"(hi)); return r; }
; #define PROBE_END(id) if (PROBE_SEC == (id)) { const unsigned long long pb_t1_ = __builtin_amdgcn_s_memrealtime(), pb_dt_ = pb_t1_ - pb_t0_##id; while (__builtin_amdgcn_s_memrealtime() - pb_t1_ < pb_dt_) __builtin_amdgcn_s_sleep(4); }
; __device__ __forceinline__ float bflo(unsigned w) { return __uint_as_float(w << 16); }
; __device__ __forceinline__ float bfhi(unsigned w) { return __uint_as_float(w & 0xffff0000u); }
; __device__ __forceinline__ float fexp2(float x) { return __builtin_amdgcn_exp2f(x); }
; __device__ __forceinline__ float half_swap_sum(float v) { const auto rr = __builtin_amdgcn_permlane32_swap(__float_as_uint(v), __float_as_uint(v), false, false); return __uint_as_float(rr[0]) + __uint_as_float(rr[1]); }
; __device__ __forceinline__ void attn_compute(Frame& F, int id) {
;     ...
; #pragma unroll
;     for (int qb = 0; qb < 2; ++qb) {
;         const float mq = qb ? m1 : m0; float lt = half_swap_sum(qb ? l1 : l0); lt += fexp2(sk - mq);
;         const float inv = 1.0f / lt; const size_t tok = tok0 + 32 * qb;
; #pragma unroll
;         for (int dh = 0; dh < 2; ++dh)
; #pragma unroll
;             for (int gq = 0; gq < 4; ++gq) {
;                 const int d = 32 * dh + 8 * gq + 4 * hh;
;                 const v2u z = *(const v2u*)(ZA + tok * 512 + h * 64 + d);
;                 const f32x16& o = qb ? O1[dh] : O0[dh];
;                 v2u w; w.x = pg8::cvt_pk_bf16(o[4 * gq + 0] * inv * bflo(z.x), o[4 * gq + 1] * inv * bfhi(z.x));
;                 w.y = pg8::cvt_pk_bf16(o[4 * gq + 2] * inv * bflo(z.y), o[4 * gq + 3] * inv * bfhi(z.y));
;                 *(v2u*)(A5 + tok * 1024 + h * 64 + d) = w;
;             }
;     }
;     PROBE_END(4)
;     __syncthreads();
	v_lshlrev_b32_e32 v4, 16, v94
	v_and_b32_e32 v5, 0xffff0000, v94
	v_lshlrev_b32_e32 v6, 16, v95
	v_and_b32_e32 v7, 0xffff0000, v95
	v_mul_f32_e32 v4, v12, v4
	v_mul_f32_e32 v5, v13, v5
	v_mul_f32_e32 v6, v14, v6
	v_mul_f32_e32 v7, v15, v7
	v_cvt_pk_bf16_f32 v94, v4, v5
	v_cvt_pk_bf16_f32 v95, v6, v7
	global_store_dwordx2 v[10:11], v[94:95], off offset:96
	v_mul_f32_e32 v12, v62, v3
	v_mul_f32_e32 v13, v63, v3
	v_mul_f32_e32 v14, v64, v3
	v_mul_f32_e32 v15, v65, v3
	s_waitcnt vmcnt(15)
	v_lshlrev_b32_e32 v4, 16, v96
	v_and_b32_e32 v5, 0xffff0000, v96
	v_lshlrev_b32_e32 v6, 16, v97
	v_and_b32_e32 v7, 0xffff0000, v97
	v_mul_f32_e32 v4, v12, v4
	v_mul_f32_e32 v5, v13, v5
	v_mul_f32_e32 v6, v14, v6
	v_mul_f32_e32 v7, v15, v7
	v_cvt_pk_bf16_f32 v96, v4, v5
	v_cvt_pk_bf16_f32 v97, v6, v7
	global_store_dwordx2 v[10:11], v[96:97], off offset:112
	v_sub_f32_e32 v8, v244, v245
	v_exp_f32_e32 v8, v8
	v_mov_b32_e32 v3, v201
	s_nop 1
	v_permlane32_swap_b32_e32 v201, v3
	v_add_f32_e32 v3, v201, v3
	v_add_f32_e32 v3, v8, v3
	v_div_scale_f32 v8, vcc, v3, v3, 1.0
	v_rcp_f32_e32 v9, v8
	v_div_scale_f32 v12, vcc, 1.0, v3, 1.0
	v_fma_f32 v13, -v8, v9, 1.0
	v_fmac_f32_e32 v9, v13, v9
	v_mul_f32_e32 v13, v12, v9
	v_fma_f32 v14, -v8, v13, v12
	v_fmac_f32_e32 v13, v14, v9
	v_fma_f32 v8, -v8, v13, v12
	v_div_fmas_f32 v8, v8, v9, v13
	v_div_fixup_f32 v3, v8, v3, 1.0
	v_mul_f32_e32 v12, v34, v3
	v_mul_f32_e32 v13, v35, v3
	v_mul_f32_e32 v14, v36, v3
	v_mul_f32_e32 v15, v37, v3
	s_waitcnt vmcnt(15)
	v_lshlrev_b32_e32 v4, 16, v98
	v_and_b32_e32 v5, 0xffff0000, v98
	v_lshlrev_b32_e32 v6, 16, v99
	v_and_b32_e32 v7, 0xffff0000, v99
	v_mul_f32_e32 v4, v12, v4
	v_mul_f32_e32 v5, v13, v5
	v_mul_f32_e32 v6, v14, v6
	v_mul_f32_e32 v7, v15, v7
	v_cvt_pk_bf16_f32 v98, v4, v5
	v_cvt_pk_bf16_f32 v99, v6, v7
	global_store_dwordx2 v[16:17], v[98:99], off
	v_mul_f32_e32 v12, v38, v3
	v_mul_f32_e32 v13, v39, v3
	v_mul_f32_e32 v14, v40, v3
	v_mul_f32_e32 v15, v41, v3
	s_waitcnt vmcnt(15)
	v_lshlrev_b32_e32 v4, 16, v100
	v_and_b32_e32 v5, 0xffff0000, v100
	v_lshlrev_b32_e32 v6, 16, v101
	v_and_b32_e32 v7, 0xffff0000, v101
	v_mul_f32_e32 v4, v12, v4
	v_mul_f32_e32 v5, v13, v5
	v_mul_f32_e32 v6, v14, v6
	v_mul_f32_e32 v7, v15, v7
	v_cvt_pk_bf16_f32 v100, v4, v5
	v_cvt_pk_bf16_f32 v101, v6, v7
	global_store_dwordx2 v[16:17], v[100:101], off offset:16
	v_mul_f32_e32 v12, v42, v3
	v_mul_f32_e32 v13, v43, v3
	v_mul_f32_e32 v14, v44, v3
	v_mul_f32_e32 v15, v45, v3
	s_waitcnt vmcnt(15)
	v_lshlrev_b32_e32 v4, 16, v102
	v_and_b32_e32 v5, 0xffff0000, v102
	v_lshlrev_b32_e32 v6, 16, v103
	v_and_b32_e32 v7, 0xffff0000, v103
	v_mul_f32_e32 v4, v12, v4
	v_mul_f32_e32 v5, v13, v5
	v_mul_f32_e32 v6, v14, v6
	v_mul_f32_e32 v7, v15, v7
	v_cvt_pk_bf16_f32 v102, v4, v5
	v_cvt_pk_bf16_f32 v103, v6, v7
	global_store_dwordx2 v[16:17], v[102:103], off offset:32
	v_mul_f32_e32 v12, v46, v3
	v_mul_f32_e32 v13, v47, v3
	v_mul_f32_e32 v14, v48, v3
	v_mul_f32_e32 v15, v49, v3
	s_waitcnt vmcnt(15)
	v_lshlrev_b32_e32 v4, 16, v104
	v_and_b32_e32 v5, 0xffff0000, v104
	v_lshlrev_b32_e32 v6, 16, v105
	v_and_b32_e32 v7, 0xffff0000, v105
	v_mul_f32_e32 v4, v12, v4
	v_mul_f32_e32 v5, v13, v5
	v_mul_f32_e32 v6, v14, v6
	v_mul_f32_e32 v7, v15, v7
	v_cvt_pk_bf16_f32 v104, v4, v5
	v_cvt_pk_bf16_f32 v105, v6, v7
	global_store_dwordx2 v[16:17], v[104:105], off offset:48
	v_mul_f32_e32 v12, v18, v3
	v_mul_f32_e32 v13, v19, v3
	v_mul_f32_e32 v14, v20, v3
	v_mul_f32_e32 v15, v21, v3
	s_waitcnt vmcnt(15)
	v_lshlrev_b32_e32 v4, 16, v106
	v_and_b32_e32 v5, 0xffff0000, v106
	v_lshlrev_b32_e32 v6, 16, v107
	v_and_b32_e32 v7, 0xffff0000, v107
	v_mul_f32_e32 v4, v12, v4
	v_mul_f32_e32 v5, v13, v5
	v_mul_f32_e32 v6, v14, v6
	v_mul_f32_e32 v7, v15, v7
	v_cvt_pk_bf16_f32 v106, v4, v5
	v_cvt_pk_bf16_f32 v107, v6, v7
	global_store_dwordx2 v[16:17], v[106:107], off offset:64
	v_mul_f32_e32 v12, v22, v3
	v_mul_f32_e32 v13, v23, v3
	v_mul_f32_e32 v14, v24, v3
	v_mul_f32_e32 v15, v25, v3
	s_waitcnt vmcnt(15)
	v_lshlrev_b32_e32 v4, 16, v108
	v_and_b32_e32 v5, 0xffff0000, v108
	v_lshlrev_b32_e32 v6, 16, v109
	v_and_b32_e32 v7, 0xffff0000, v109
	v_mul_f32_e32 v4, v12, v4
	v_mul_f32_e32 v5, v13, v5
	v_mul_f32_e32 v6, v14, v6
	v_mul_f32_e32 v7, v15, v7
	v_cvt_pk_bf16_f32 v108, v4, v5
	v_cvt_pk_bf16_f32 v109, v6, v7
	global_store_dwordx2 v[16:17], v[108:109], off offset:80
	v_mul_f32_e32 v12, v26, v3
	v_mul_f32_e32 v13, v27, v3
	v_mul_f32_e32 v14, v28, v3
	v_mul_f32_e32 v15, v29, v3
	s_waitcnt vmcnt(15)
	v_lshlrev_b32_e32 v4, 16, v110
	v_and_b32_e32 v5, 0xffff0000, v110
	v_lshlrev_b32_e32 v6, 16, v111
	v_and_b32_e32 v7, 0xffff0000, v111
	v_mul_f32_e32 v4, v12, v4
	v_mul_f32_e32 v5, v13, v5
	v_mul_f32_e32 v6, v14, v6
	v_mul_f32_e32 v7, v15, v7
	v_cvt_pk_bf16_f32 v110, v4, v5
	v_cvt_pk_bf16_f32 v111, v6, v7
	global_store_dwordx2 v[16:17], v[110:111], off offset:96
	v_mul_f32_e32 v12, v30, v3
	v_mul_f32_e32 v13, v31, v3
	v_mul_f32_e32 v14, v32, v3
	v_mul_f32_e32 v15, v33, v3
	s_waitcnt vmcnt(15)
	v_lshlrev_b32_e32 v4, 16, v112
	v_and_b32_e32 v5, 0xffff0000, v112
	v_lshlrev_b32_e32 v6, 16, v113
	v_and_b32_e32 v7, 0xffff0000, v113
	v_mul_f32_e32 v4, v12, v4
	v_mul_f32_e32 v5, v13, v5
	v_mul_f32_e32 v6, v14, v6
	v_mul_f32_e32 v7, v15, v7
	v_cvt_pk_bf16_f32 v112, v4, v5
	v_cvt_pk_bf16_f32 v113, v6, v7
	global_store_dwordx2 v[16:17], v[112:113], off offset:112
	s_andn2_b64 vcc, exec, s[2:3]
	s_barrier
	s_cbranch_vccz .LBB0_580

; #define LAS __attribute__((address_space(3)))
; __device__ __forceinline__ float fexp2(float x) { return __builtin_amdgcn_exp2f(x); }
; __device__ __forceinline__ float half_swap_max(float v) { const auto rr = __builtin_amdgcn_permlane32_swap(__float_as_uint(v), __float_as_uint(v), false, false); return fmaxf(__uint_as_float(rr[0]), __uint_as_float(rr[1])); }
; __device__ __forceinline__ void softmax_pv(f32x16& a, float& m, float& l, f32x16 (&O)[2], const LAS unsigned char* vp) {
;     float t0 = fmaxf(a[0], a[1]), t1 = fmaxf(a[2], a[3]);
; #pragma unroll
;     for (int q = 4; q < 16; q += 4) { t0 = fmaxf(t0, fmaxf(a[q], a[q + 1])); t1 = fmaxf(t1, fmaxf(a[q + 2], a[q + 3])); }
;     const float tmax = half_swap_max(fmaxf(t0, t1));
;     if (__any(tmax > m + THR)) {
;         const float mn = tmax > m + THR ? tmax : m, sc = fexp2(m - mn);
;         O[0] = O[0] * sc; O[1] = O[1] * sc; l *= sc; m = mn;
; __device__ __forceinline__ void attn_compute(Frame& F, int id) {
;     ...
;     for (int j = 0; j < 9; ++j) {
;         const int p0 = key0 + 32 * (ktA + j), p1 = p0 + 32;
;         f32x16 c;
; #pragma unroll
;         for (int jj = 0; jj < 4; ++jj) { const f32x4 bv = BTg[32 * j + 8 * jj]; c[4 * jj] = bv[0]; c[4 * jj + 1] = bv[1]; c[4 * jj + 2] = bv[2]; c[4 * jj + 3] = bv[3]; }
;         f32x16 a0 = c, a1 = c;
;         if (p0 < 0 || p0 >= SEQ) {
; #pragma unroll
;             for (int q = 0; q < 16; ++q) a0[q] = -1e30f; }
;         if (p1 < 0 || p1 >= SEQ) {
; #pragma unroll
;             for (int q = 0; q < 16; ++q) a1[q] = -1e30f; }
;         const LAS unsigned char* k0 = kbase + j * 32 * KROW;
; #pragma unroll
;         for (int st = 0; st < 4; ++st) a0 = __builtin_amdgcn_mfma_f32_32x32x16_bf16(*(const LAS bf16x8*)(k0 + st * 32), qf[0][st], a0, 0, 0, 0);
; #pragma unroll
;         for (int st = 0; st < 4; ++st) a1 = __builtin_amdgcn_mfma_f32_32x32x16_bf16(*(const LAS bf16x8*)(k0 + 32 * KROW + st * 32), qf[1][st], a1, 0, 0, 0);
.LBB0_576:
	v_add_u32_e32 v3, 0x19df0, v203
	v_add_u32_e32 v16, 0x13900, v248
	v_add_u32_e32 v17, 0xd800, v248
	ds_read_b128 v[98:101], v3
	ds_read_b128 v[102:105], v3 offset:128
	ds_read_b128 v[106:109], v3 offset:256
	ds_read_b128 v[110:113], v3 offset:384
	ds_read_b128 v[4:7], v247
	ds_read_b128 v[8:11], v247 offset:32
	ds_read_b128 v[82:85], v3
	ds_read_b128 v[86:89], v3 offset:128
	ds_read_b128 v[90:93], v3 offset:256
	ds_read_b128 v[94:97], v3 offset:384
	ds_read_b128 v[12:15], v247 offset:64
	s_add_i32 s4, s23, s14
	s_add_i32 s5, s4, 0xa0
	s_addk_i32 s4, 0xf8c0
	s_cmpk_lt_u32 s5, 0x800
	s_cbranch_scc0 .Lattn_fix_a0
.Lattn_a0_ok:
	s_cmp_gt_u32 s4, 0xfffff7ff
	s_cbranch_scc0 .Lattn_fix_a1
.Lattn_a1_ok:
	s_waitcnt vmcnt(7) lgkmcnt(6)
	v_mfma_f32_32x32x16_bf16 v[98:113], v[4:7], v[162:165], v[98:113]
	ds_read_b128 v[4:7], v247 offset:96
	s_waitcnt vmcnt(6) lgkmcnt(6)
	v_mfma_f32_32x32x16_bf16 v[98:113], v[8:11], v[166:169], v[98:113]
	ds_read_b128 v[8:11], v247 offset:4608
	s_waitcnt vmcnt(5) lgkmcnt(2)
	v_mfma_f32_32x32x16_bf16 v[98:113], v[12:15], v[170:173], v[98:113]
	ds_read_b128 v[12:15], v247 offset:4640
	s_waitcnt vmcnt(4) lgkmcnt(2)
	v_mfma_f32_32x32x16_bf16 v[98:113], v[4:7], v[174:177], v[98:113]
	ds_read_b128 v[4:7], v247 offset:4672
	s_waitcnt vmcnt(3) lgkmcnt(2)
	v_mfma_f32_32x32x16_bf16 v[82:97], v[8:11], v[178:181], v[82:97]
	ds_read_b128 v[8:11], v247 offset:4704
	s_waitcnt vmcnt(2) lgkmcnt(2)
	v_mfma_f32_32x32x16_bf16 v[82:97], v[12:15], v[182:185], v[82:97]
	s_waitcnt vmcnt(1) lgkmcnt(1)
	v_mfma_f32_32x32x16_bf16 v[82:97], v[4:7], v[186:189], v[82:97]
	s_waitcnt vmcnt(0) lgkmcnt(0)
	v_mfma_f32_32x32x16_bf16 v[82:97], v[8:11], v[190:193], v[82:97]
	v_add_u32_e32 v203, 0x200, v203
	v_add_u32_e32 v247, 0x1200, v247
	v_add_u32_e32 v248, 64, v248
	s_add_i32 s14, s14, 32
	v_max3_f32 v3, v98, v99, v100
	v_max3_f32 v4, v101, v102, v103
	v_max3_f32 v5, v104, v105, v106
	v_max3_f32 v6, v107, v108, v109
	v_max3_f32 v7, v110, v111, v112
	v_max3_f32 v3, v3, v4, v5
	v_max3_f32 v4, v6, v7, v113
	v_max_f32_e32 v3, v3, v4
	v_mov_b32_e32 v4, v3
	s_nop 1
	v_permlane32_swap_b32_e32 v3, v4
	v_max_f32_e32 v3, v3, v4
	v_cmp_gt_f32_e32 vcc, v3, v249
	s_cbranch_vccz .Lattn_nors_s0
	s_nop 0
	v_cndmask_b32_e32 v3, v249, v3, vcc
	v_sub_f32_e32 v4, v249, v3
	v_exp_f32_e32 v4, v4
	v_mov_b32_e32 v249, v3
	v_pk_mul_f32 v[80:81], v[80:81], v[4:5] op_sel_hi:[1,0]
	v_pk_mul_f32 v[78:79], v[78:79], v[4:5] op_sel_hi:[1,0]
	v_pk_mul_f32 v[76:77], v[76:77], v[4:5] op_sel_hi:[1,0]
	v_pk_mul_f32 v[74:75], v[74:75], v[4:5] op_sel_hi:[1,0]
	v_pk_mul_f32 v[72:73], v[72:73], v[4:5] op_sel_hi:[1,0]
	v_pk_mul_f32 v[70:71], v[70:71], v[4:5] op_sel_hi:[1,0]
	v_pk_mul_f32 v[68:69], v[68:69], v[4:5] op_sel_hi:[1,0]
	v_pk_mul_f32 v[66:67], v[66:67], v[4:5] op_sel_hi:[1,0]
	v_pk_mul_f32 v[64:65], v[64:65], v[4:5] op_sel_hi:[1,0]
	v_pk_mul_f32 v[62:63], v[62:63], v[4:5] op_sel_hi:[1,0]
	v_pk_mul_f32 v[60:61], v[60:61], v[4:5] op_sel_hi:[1,0]
	v_pk_mul_f32 v[58:59], v[58:59], v[4:5] op_sel_hi:[1,0]
	v_pk_mul_f32 v[56:57], v[56:57], v[4:5] op_sel_hi:[1,0]
	v_pk_mul_f32 v[54:55], v[54:55], v[4:5] op_sel_hi:[1,0]
	v_pk_mul_f32 v[52:53], v[52:53], v[4:5] op_sel_hi:[1,0]
	v_pk_mul_f32 v[50:51], v[50:51], v[4:5] op_sel_hi:[1,0]
	v_mul_f32_e32 v246, v246, v4
; __device__ __forceinline__ unsigned cvt_pk_bf16(float lo, float hi) { unsigned r; asm volatile("v_cvt_pk_bf16_f32 %0, %1, %2" : "=v"(r) : "v"(lo), "v"(hi)); return r; }
; #define LAS __attribute__((address_space(3)))
; __device__ __forceinline__ float fexp2(float x) { return __builtin_amdgcn_exp2f(x); }
; __device__ __forceinline__ float half_swap_max(float v) { const auto rr = __builtin_amdgcn_permlane32_swap(__float_as_uint(v), __float_as_uint(v), false, false); return fmaxf(__uint_as_float(rr[0]), __uint_as_float(rr[1])); }
; __device__ __forceinline__ void softmax_pv(f32x16& a, float& m, float& l, f32x16 (&O)[2], const LAS unsigned char* vp) {
;     ...
;     const float tmax = half_swap_max(fmaxf(t0, t1));
;     if (__any(tmax > m + THR)) {
;         const float mn = tmax > m + THR ? tmax : m, sc = fexp2(m - mn);
;         O[0] = O[0] * sc; O[1] = O[1] * sc; l *= sc; m = mn;
;     }
;     float ls = 0.f;
; #pragma unroll
;     for (int q = 0; q < 16; ++q) { const float p = fexp2(a[q] - m); a[q] = p; ls += p; }
;     l += ls;
; #pragma unroll
;     for (int s2 = 0; s2 < 2; ++s2) {
;         v4u pw; pw.x = pg8::cvt_pk_bf16(a[8 * s2 + 0], a[8 * s2 + 1]); pw.y = pg8::cvt_pk_bf16(a[8 * s2 + 2], a[8 * s2 + 3]);
;         pw.z = pg8::cvt_pk_bf16(a[8 * s2 + 4], a[8 * s2 + 5]); pw.w = pg8::cvt_pk_bf16(a[8 * s2 + 6], a[8 * s2 + 7]);
;         const bf16x8 pf = __builtin_bit_cast(bf16x8, pw);
; #pragma unroll
;         for (int dh = 0; dh < 2; ++dh) { const LAS unsigned char* v = vp + dh * 32 * VROW + 32 * s2;
;             const v2u v0 = *(const LAS v2u*)v, v1 = *(const LAS v2u*)(v + 16);
;             O[dh] = __builtin_amdgcn_mfma_f32_32x32x16_bf16(__builtin_bit_cast(bf16x8, (v4u){v0.x, v0.y, v1.x, v1.y}), pf, O[dh], 0, 0, 0); }
;     }
; __device__ __forceinline__ void attn_compute(Frame& F, int id) {
;     ...
;         softmax_pv(a0, m0, l0, O0, vbase + 64 * j);
;         softmax_pv(a1, m1, l1, O1, vbase + 64 * j + 64);
.Lattn_nors_s0:
	ds_read2_b64 v[4:7], v17 offset0:0 offset1:2
	ds_read2_b64 v[8:11], v16 offset0:0 offset1:2
	v_sub_f32_e32 v98, v98, v249
	v_sub_f32_e32 v99, v99, v249
	v_exp_f32_e32 v98, v98
	v_sub_f32_e32 v100, v100, v249
	v_exp_f32_e32 v99, v99
	v_sub_f32_e32 v101, v101, v249
	v_exp_f32_e32 v100, v100
	v_sub_f32_e32 v102, v102, v249
	v_exp_f32_e32 v101, v101
	v_sub_f32_e32 v103, v103, v249
	v_exp_f32_e32 v102, v102
	v_sub_f32_e32 v104, v104, v249
	v_exp_f32_e32 v103, v103
	v_sub_f32_e32 v105, v105, v249
	v_exp_f32_e32 v104, v104
	v_exp_f32_e32 v105, v105
	v_cvt_pk_bf16_f32 v12, v98, v99
	v_cvt_pk_bf16_f32 v13, v100, v101
	v_cvt_pk_bf16_f32 v14, v102, v103
	v_add_f32_e32 v3, v98, v99
	v_cvt_pk_bf16_f32 v15, v104, v105
	v_add_f32_e32 v3, v100, v3
	v_add_f32_e32 v3, v101, v3
	v_add_f32_e32 v3, v102, v3
	v_add_f32_e32 v3, v103, v3
	v_add_f32_e32 v3, v104, v3
	v_add_f32_e32 v3, v105, v3
	s_waitcnt lgkmcnt(1)
	v_mfma_f32_32x32x16_bf16 v[66:81], v[4:7], v[12:15], v[66:81]
	s_waitcnt lgkmcnt(0)
	v_mfma_f32_32x32x16_bf16 v[50:65], v[8:11], v[12:15], v[50:65]
	ds_read2_b64 v[98:101], v17 offset0:4 offset1:6
	ds_read2_b64 v[102:105], v16 offset0:4 offset1:6
	v_sub_f32_e32 v106, v106, v249
	v_sub_f32_e32 v107, v107, v249
	v_exp_f32_e32 v106, v106
	v_sub_f32_e32 v108, v108, v249
	v_exp_f32_e32 v107, v107
	v_sub_f32_e32 v109, v109, v249
	v_exp_f32_e32 v108, v108
	v_sub_f32_e32 v110, v110, v249
	v_exp_f32_e32 v109, v109
	v_sub_f32_e32 v111, v111, v249
	v_exp_f32_e32 v110, v110
	v_sub_f32_e32 v112, v112, v249
	v_exp_f32_e32 v111, v111
	v_sub_f32_e32 v113, v113, v249
	v_exp_f32_e32 v112, v112
	v_exp_f32_e32 v113, v113
	v_cvt_pk_bf16_f32 v4, v106, v107
	v_cvt_pk_bf16_f32 v5, v108, v109
	v_cvt_pk_bf16_f32 v6, v110, v111
	v_cvt_pk_bf16_f32 v7, v112, v113
	v_add_f32_e32 v3, v106, v3
	v_add_f32_e32 v3, v107, v3
	v_add_f32_e32 v3, v108, v3
	v_add_f32_e32 v3, v109, v3
	v_add_f32_e32 v3, v110, v3
	v_add_f32_e32 v3, v111, v3
	v_add_f32_e32 v3, v112, v3
	v_add_f32_e32 v3, v113, v3
	v_add_f32_e32 v246, v246, v3
	s_waitcnt lgkmcnt(1)
	v_mfma_f32_32x32x16_bf16 v[66:81], v[98:101], v[4:7], v[66:81]
	s_waitcnt lgkmcnt(0)
	v_mfma_f32_32x32x16_bf16 v[50:65], v[102:105], v[4:7], v[50:65]
	v_max3_f32 v3, v82, v83, v84
	v_max3_f32 v4, v85, v86, v87
	v_max3_f32 v5, v88, v89, v90
	v_max3_f32 v6, v91, v92, v93
	v_max3_f32 v7, v94, v95, v96
	v_max3_f32 v3, v3, v4, v5
	v_max3_f32 v4, v6, v7, v97
	v_max_f32_e32 v3, v3, v4
	v_mov_b32_e32 v4, v3
	s_nop 1
	v_permlane32_swap_b32_e32 v3, v4
	v_max_f32_e32 v3, v3, v4
	v_cmp_gt_f32_e32 vcc, v3, v245
	s_cbranch_vccz .Lattn_nors_s1
	s_nop 0
	v_cndmask_b32_e32 v3, v245, v3, vcc
	v_sub_f32_e32 v4, v245, v3
	v_exp_f32_e32 v4, v4
	v_mov_b32_e32 v245, v3
	v_pk_mul_f32 v[48:49], v[48:49], v[4:5] op_sel_hi:[1,0]
	v_pk_mul_f32 v[46:47], v[46:47], v[4:5] op_sel_hi:[1,0]
	v_pk_mul_f32 v[44:45], v[44:45], v[4:5] op_sel_hi:[1,0]
	v_pk_mul_f32 v[42:43], v[42:43], v[4:5] op_sel_hi:[1,0]
	v_pk_mul_f32 v[40:41], v[40:41], v[4:5] op_sel_hi:[1,0]
	v_pk_mul_f32 v[38:39], v[38:39], v[4:5] op_sel_hi:[1,0]
	v_pk_mul_f32 v[36:37], v[36:37], v[4:5] op_sel_hi:[1,0]
	v_pk_mul_f32 v[34:35], v[34:35], v[4:5] op_sel_hi:[1,0]
	v_pk_mul_f32 v[32:33], v[32:33], v[4:5] op_sel_hi:[1,0]
	v_pk_mul_f32 v[30:31], v[30:31], v[4:5] op_sel_hi:[1,0]
	v_pk_mul_f32 v[28:29], v[28:29], v[4:5] op_sel_hi:[1,0]
	v_pk_mul_f32 v[26:27], v[26:27], v[4:5] op_sel_hi:[1,0]
	v_pk_mul_f32 v[24:25], v[24:25], v[4:5] op_sel_hi:[1,0]
	v_pk_mul_f32 v[22:23], v[22:23], v[4:5] op_sel_hi:[1,0]
	v_pk_mul_f32 v[20:21], v[20:21], v[4:5] op_sel_hi:[1,0]
	v_pk_mul_f32 v[18:19], v[18:19], v[4:5] op_sel_hi:[1,0]
	v_mul_f32_e32 v201, v201, v4
.Lattn_nors_s1:
	ds_read2_b64 v[4:7], v17 offset0:8 offset1:10
	ds_read2_b64 v[8:11], v16 offset0:8 offset1:10
	v_sub_f32_e32 v82, v82, v245
	v_sub_f32_e32 v83, v83, v245
	v_exp_f32_e32 v82, v82
	v_sub_f32_e32 v84, v84, v245
	v_exp_f32_e32 v83, v83
	v_sub_f32_e32 v85, v85, v245
	v_exp_f32_e32 v84, v84
	v_sub_f32_e32 v86, v86, v245
	v_exp_f32_e32 v85, v85
	v_sub_f32_e32 v87, v87, v245
	v_exp_f32_e32 v86, v86
	v_sub_f32_e32 v88, v88, v245
	v_exp_f32_e32 v87, v87
	v_sub_f32_e32 v89, v89, v245
	v_exp_f32_e32 v88, v88
	v_exp_f32_e32 v89, v89
	v_cvt_pk_bf16_f32 v12, v82, v83
	v_cvt_pk_bf16_f32 v13, v84, v85
	v_cvt_pk_bf16_f32 v14, v86, v87
	v_add_f32_e32 v3, v82, v83
	v_cvt_pk_bf16_f32 v15, v88, v89
	v_add_f32_e32 v3, v84, v3
	v_add_f32_e32 v3, v85, v3
	v_add_f32_e32 v3, v86, v3
	v_add_f32_e32 v3, v87, v3
	v_add_f32_e32 v3, v88, v3
	v_add_f32_e32 v3, v89, v3
	s_waitcnt lgkmcnt(1)
	v_mfma_f32_32x32x16_bf16 v[34:49], v[4:7], v[12:15], v[34:49]
	s_waitcnt lgkmcnt(0)
	v_mfma_f32_32x32x16_bf16 v[18:33], v[8:11], v[12:15], v[18:33]
	ds_read2_b64 v[82:85], v17 offset0:12 offset1:14
	ds_read2_b64 v[86:89], v16 offset0:12 offset1:14
	v_sub_f32_e32 v90, v90, v245
	v_sub_f32_e32 v91, v91, v245
	v_exp_f32_e32 v90, v90
	v_sub_f32_e32 v92, v92, v245
	v_exp_f32_e32 v91, v91
	v_sub_f32_e32 v93, v93, v245
	v_exp_f32_e32 v92, v92
	v_sub_f32_e32 v94, v94, v245
	v_exp_f32_e32 v93, v93
	v_sub_f32_e32 v95, v95, v245
	v_exp_f32_e32 v94, v94
	v_sub_f32_e32 v96, v96, v245
	v_exp_f32_e32 v95, v95
	v_sub_f32_e32 v97, v97, v245
	v_exp_f32_e32 v96, v96
	v_exp_f32_e32 v97, v97
	v_cvt_pk_bf16_f32 v4, v90, v91
	v_cvt_pk_bf16_f32 v5, v92, v93
	v_cvt_pk_bf16_f32 v6, v94, v95
	v_cvt_pk_bf16_f32 v7, v96, v97
	v_add_f32_e32 v3, v90, v3
	v_add_f32_e32 v3, v91, v3
	v_add_f32_e32 v3, v92, v3
	v_add_f32_e32 v3, v93, v3
	v_add_f32_e32 v3, v94, v3
	v_add_f32_e32 v3, v95, v3
	v_add_f32_e32 v3, v96, v3
	v_add_f32_e32 v3, v97, v3
	v_add_f32_e32 v201, v201, v3
	s_waitcnt lgkmcnt(1)
	v_mfma_f32_32x32x16_bf16 v[34:49], v[82:85], v[4:7], v[34:49]
	s_waitcnt lgkmcnt(0)
	v_mfma_f32_32x32x16_bf16 v[18:33], v[86:89], v[4:7], v[18:33]
	s_cmp_lg_u32 s14, 0
	s_cbranch_scc1 .LBB0_576
	s_branch .LBB0_544
.Lattn_fix_a0:
	s_waitcnt lgkmcnt(0)
	v_mov_b32_e32 v98, v243
	v_mov_b32_e32 v99, v243
	v_mov_b32_e32 v100, v243
	v_mov_b32_e32 v101, v243
	v_mov_b32_e32 v102, v243
	v_mov_b32_e32 v103, v243
	v_mov_b32_e32 v104, v243
	v_mov_b32_e32 v105, v243
	v_mov_b32_e32 v106, v243
	v_mov_b32_e32 v107, v243
	v_mov_b32_e32 v108, v243
	v_mov_b32_e32 v109, v243
	v_mov_b32_e32 v110, v243
	v_mov_b32_e32 v111, v243
	v_mov_b32_e32 v112, v243
	v_mov_b32_e32 v113, v243
	s_branch .Lattn_a0_ok
.Lattn_fix_a1:
	s_waitcnt lgkmcnt(0)
	v_mov_b32_e32 v82, v243
	v_mov_b32_e32 v83, v243
	v_mov_b32_e32 v84, v243
	v_mov_b32_e32 v85, v243
	v_mov_b32_e32 v86, v243
	v_mov_b32_e32 v87, v243
	v_mov_b32_e32 v88, v243
	v_mov_b32_e32 v89, v243
	v_mov_b32_e32 v90, v243
	v_mov_b32_e32 v91, v243
	v_mov_b32_e32 v92, v243
	v_mov_b32_e32 v93, v243
	v_mov_b32_e32 v94, v243
	v_mov_b32_e32 v95, v243
	v_mov_b32_e32 v96, v243
	v_mov_b32_e32 v97, v243
	s_branch .Lattn_a1_ok
